# removed 8 compiler-inserted preheader vmcnt(0) drains (6 GEMM unit tops, 2 attention tile-loop entries)
# speedup vs baseline: 1.0073x; 1.0073x over previous
.LBB0_130:
	s_ashr_i32 s17, s16, 31
	s_lshl_b64 s[24:25], s[16:17], 21
	s_add_u32 s24, s44, s24
	s_addc_u32 s25, s45, s25
	s_and_b64 s[26:27], s[22:23], exec
	s_cselect_b32 s7, s25, s35
	s_cselect_b32 s17, s24, s34
	s_ashr_i32 s21, s20, 31
	s_lshl_b64 s[26:27], s[20:21], 21
	s_add_u32 s26, s46, s26
	s_addc_u32 s27, s47, s27
	s_and_b64 s[36:37], s[22:23], exec
	s_cselect_b32 s21, s27, s31
	s_cselect_b32 s33, s26, s30
	s_add_u32 s55, s30, 0x100
	s_addc_u32 s56, s31, 0
	s_add_u32 s57, s34, 0x100
	v_mov_b32_e32 v6, 0
	s_addc_u32 s58, s35, 0
	s_mov_b32 s59, -2
	v_mov_b32_e32 v7, v6
	v_mov_b32_e32 v8, v6
	v_mov_b32_e32 v9, v6
	v_mov_b32_e32 v10, v6
	v_mov_b32_e32 v11, v6
	v_mov_b32_e32 v12, v6
	v_mov_b32_e32 v13, v6
	v_mov_b32_e32 v22, v6
	v_mov_b32_e32 v23, v6
	v_mov_b32_e32 v24, v6
	v_mov_b32_e32 v25, v6
	v_mov_b32_e32 v26, v6
	v_mov_b32_e32 v27, v6
	v_mov_b32_e32 v28, v6
	v_mov_b32_e32 v29, v6
	v_mov_b32_e32 v38, v6
	v_mov_b32_e32 v39, v6
	v_mov_b32_e32 v40, v6
	v_mov_b32_e32 v41, v6
	v_mov_b32_e32 v42, v6
	v_mov_b32_e32 v43, v6
	v_mov_b32_e32 v44, v6
	v_mov_b32_e32 v45, v6
	v_mov_b32_e32 v54, v6
	v_mov_b32_e32 v55, v6
	v_mov_b32_e32 v56, v6
	v_mov_b32_e32 v57, v6
	v_mov_b32_e32 v58, v6
	v_mov_b32_e32 v59, v6
	v_mov_b32_e32 v60, v6
	v_mov_b32_e32 v61, v6
	v_mov_b32_e32 v14, v6
	v_mov_b32_e32 v15, v6
	v_mov_b32_e32 v16, v6
	v_mov_b32_e32 v17, v6
	v_mov_b32_e32 v18, v6
	v_mov_b32_e32 v19, v6
	v_mov_b32_e32 v20, v6
	v_mov_b32_e32 v21, v6
	v_mov_b32_e32 v30, v6
	v_mov_b32_e32 v31, v6
	v_mov_b32_e32 v32, v6
	v_mov_b32_e32 v33, v6
	v_mov_b32_e32 v34, v6
	v_mov_b32_e32 v35, v6
	v_mov_b32_e32 v36, v6
	v_mov_b32_e32 v37, v6
	v_mov_b32_e32 v46, v6
	v_mov_b32_e32 v47, v6
	v_mov_b32_e32 v48, v6
	v_mov_b32_e32 v49, v6
	v_mov_b32_e32 v50, v6
	v_mov_b32_e32 v51, v6
	v_mov_b32_e32 v52, v6
	v_mov_b32_e32 v53, v6
	v_mov_b32_e32 v62, v6
	v_mov_b32_e32 v63, v6
	v_mov_b32_e32 v64, v6
	v_mov_b32_e32 v65, v6
	v_mov_b32_e32 v66, v6
	v_mov_b32_e32 v67, v6
	v_mov_b32_e32 v68, v6
	v_mov_b32_e32 v69, v6
	v_mov_b32_e32 v70, v6
	v_mov_b32_e32 v71, v6
	v_mov_b32_e32 v72, v6
	v_mov_b32_e32 v73, v6
	v_mov_b32_e32 v74, v6
	v_mov_b32_e32 v75, v6
	v_mov_b32_e32 v76, v6
	v_mov_b32_e32 v77, v6
	v_mov_b32_e32 v86, v6
	v_mov_b32_e32 v87, v6
	v_mov_b32_e32 v88, v6
	v_mov_b32_e32 v89, v6
	v_mov_b32_e32 v90, v6
	v_mov_b32_e32 v91, v6
	v_mov_b32_e32 v92, v6
	v_mov_b32_e32 v93, v6
	v_mov_b32_e32 v102, v6
	v_mov_b32_e32 v103, v6
	v_mov_b32_e32 v104, v6
	v_mov_b32_e32 v105, v6
	v_mov_b32_e32 v106, v6
	v_mov_b32_e32 v107, v6
	v_mov_b32_e32 v108, v6
	v_mov_b32_e32 v109, v6
	v_mov_b32_e32 v118, v6
	v_mov_b32_e32 v119, v6
	v_mov_b32_e32 v120, v6
	v_mov_b32_e32 v121, v6
	v_mov_b32_e32 v122, v6
	v_mov_b32_e32 v123, v6
	v_mov_b32_e32 v124, v6
	v_mov_b32_e32 v125, v6
	v_mov_b32_e32 v78, v6
	v_mov_b32_e32 v79, v6
	v_mov_b32_e32 v80, v6
	v_mov_b32_e32 v81, v6
	v_mov_b32_e32 v82, v6
	v_mov_b32_e32 v83, v6
	v_mov_b32_e32 v84, v6
	v_mov_b32_e32 v85, v6
	v_mov_b32_e32 v94, v6
	v_mov_b32_e32 v95, v6
	v_mov_b32_e32 v96, v6
	v_mov_b32_e32 v97, v6
	v_mov_b32_e32 v98, v6
	v_mov_b32_e32 v99, v6
	v_mov_b32_e32 v100, v6
	v_mov_b32_e32 v101, v6
	v_mov_b32_e32 v110, v6
	v_mov_b32_e32 v111, v6
	v_mov_b32_e32 v112, v6
	v_mov_b32_e32 v113, v6
	v_mov_b32_e32 v114, v6
	v_mov_b32_e32 v115, v6
	v_mov_b32_e32 v116, v6
	v_mov_b32_e32 v117, v6
	v_mov_b32_e32 v126, v6
	v_mov_b32_e32 v127, v6
	v_mov_b32_e32 v128, v6
	v_mov_b32_e32 v129, v6
	v_mov_b32_e32 v130, v6
	v_mov_b32_e32 v131, v6
	v_mov_b32_e32 v132, v6
	v_mov_b32_e32 v133, v6

.LBB0_250:
	s_ashr_i32 s11, s10, 31
	s_lshl_b64 s[16:17], s[10:11], 21
	s_add_u32 s16, s44, s16
	s_addc_u32 s17, s45, s17
	s_and_b64 s[20:21], s[28:29], exec
	s_cselect_b32 s1, s17, s27
	s_cselect_b32 s2, s16, s26
	s_ashr_i32 s15, s14, 31
	s_lshl_b64 s[20:21], s[14:15], 21
	s_add_u32 s20, s38, s20
	s_addc_u32 s21, s39, s21
	s_and_b64 s[28:29], s[28:29], exec
	s_cselect_b32 s11, s21, s25
	s_cselect_b32 s15, s20, s24
	s_add_u32 s19, s24, 0x100
	s_addc_u32 s33, s25, 0
	s_add_u32 s52, s26, 0x100
	v_mov_b32_e32 v118, 0
	s_addc_u32 s53, s27, 0
	s_mov_b32 s54, -2
	v_mov_b32_e32 v119, v118
	v_mov_b32_e32 v120, v118
	v_mov_b32_e32 v121, v118
	v_mov_b32_e32 v122, v118
	v_mov_b32_e32 v123, v118
	v_mov_b32_e32 v124, v118
	v_mov_b32_e32 v125, v118
	v_mov_b32_e32 v114, v118
	v_mov_b32_e32 v115, v118
	v_mov_b32_e32 v116, v118
	v_mov_b32_e32 v117, v118
	v_mov_b32_e32 v110, v118
	v_mov_b32_e32 v111, v118
	v_mov_b32_e32 v112, v118
	v_mov_b32_e32 v113, v118
	v_mov_b32_e32 v98, v118
	v_mov_b32_e32 v99, v118
	v_mov_b32_e32 v100, v118
	v_mov_b32_e32 v101, v118
	v_mov_b32_e32 v94, v118
	v_mov_b32_e32 v95, v118
	v_mov_b32_e32 v96, v118
	v_mov_b32_e32 v97, v118
	v_mov_b32_e32 v82, v118
	v_mov_b32_e32 v83, v118
	v_mov_b32_e32 v84, v118
	v_mov_b32_e32 v85, v118
	v_mov_b32_e32 v78, v118
	v_mov_b32_e32 v79, v118
	v_mov_b32_e32 v80, v118
	v_mov_b32_e32 v81, v118
	v_mov_b32_e32 v126, v118
	v_mov_b32_e32 v127, v118
	v_mov_b32_e32 v128, v118
	v_mov_b32_e32 v129, v118
	v_mov_b32_e32 v130, v118
	v_mov_b32_e32 v131, v118
	v_mov_b32_e32 v132, v118
	v_mov_b32_e32 v133, v118
	v_mov_b32_e32 v106, v118
	v_mov_b32_e32 v107, v118
	v_mov_b32_e32 v108, v118
	v_mov_b32_e32 v109, v118
	v_mov_b32_e32 v102, v118
	v_mov_b32_e32 v103, v118
	v_mov_b32_e32 v104, v118
	v_mov_b32_e32 v105, v118
	v_mov_b32_e32 v90, v118
	v_mov_b32_e32 v91, v118
	v_mov_b32_e32 v92, v118
	v_mov_b32_e32 v93, v118
	v_mov_b32_e32 v86, v118
	v_mov_b32_e32 v87, v118
	v_mov_b32_e32 v88, v118
	v_mov_b32_e32 v89, v118
	v_mov_b32_e32 v74, v118
	v_mov_b32_e32 v75, v118
	v_mov_b32_e32 v76, v118
	v_mov_b32_e32 v77, v118
	v_mov_b32_e32 v70, v118
	v_mov_b32_e32 v71, v118
	v_mov_b32_e32 v72, v118
	v_mov_b32_e32 v73, v118
	v_mov_b32_e32 v66, v118
	v_mov_b32_e32 v67, v118
	v_mov_b32_e32 v68, v118
	v_mov_b32_e32 v69, v118
	v_mov_b32_e32 v62, v118
	v_mov_b32_e32 v63, v118
	v_mov_b32_e32 v64, v118
	v_mov_b32_e32 v65, v118
	v_mov_b32_e32 v50, v118
	v_mov_b32_e32 v51, v118
	v_mov_b32_e32 v52, v118
	v_mov_b32_e32 v53, v118
	v_mov_b32_e32 v46, v118
	v_mov_b32_e32 v47, v118
	v_mov_b32_e32 v48, v118
	v_mov_b32_e32 v49, v118
	v_mov_b32_e32 v34, v118
	v_mov_b32_e32 v35, v118
	v_mov_b32_e32 v36, v118
	v_mov_b32_e32 v37, v118
	v_mov_b32_e32 v30, v118
	v_mov_b32_e32 v31, v118
	v_mov_b32_e32 v32, v118
	v_mov_b32_e32 v33, v118
	v_mov_b32_e32 v18, v118
	v_mov_b32_e32 v19, v118
	v_mov_b32_e32 v20, v118
	v_mov_b32_e32 v21, v118
	v_mov_b32_e32 v14, v118
	v_mov_b32_e32 v15, v118
	v_mov_b32_e32 v16, v118
	v_mov_b32_e32 v17, v118
	v_mov_b32_e32 v58, v118
	v_mov_b32_e32 v59, v118
	v_mov_b32_e32 v60, v118
	v_mov_b32_e32 v61, v118
	v_mov_b32_e32 v54, v118
	v_mov_b32_e32 v55, v118
	v_mov_b32_e32 v56, v118
	v_mov_b32_e32 v57, v118
	v_mov_b32_e32 v42, v118
	v_mov_b32_e32 v43, v118
	v_mov_b32_e32 v44, v118
	v_mov_b32_e32 v45, v118
	v_mov_b32_e32 v38, v118
	v_mov_b32_e32 v39, v118
	v_mov_b32_e32 v40, v118
	v_mov_b32_e32 v41, v118
	v_mov_b32_e32 v26, v118
	v_mov_b32_e32 v27, v118
	v_mov_b32_e32 v28, v118
	v_mov_b32_e32 v29, v118
	v_mov_b32_e32 v22, v118
	v_mov_b32_e32 v23, v118
	v_mov_b32_e32 v24, v118
	v_mov_b32_e32 v25, v118
	v_mov_b32_e32 v10, v118
	v_mov_b32_e32 v11, v118
	v_mov_b32_e32 v12, v118
	v_mov_b32_e32 v13, v118
	v_mov_b32_e32 v6, v118
	v_mov_b32_e32 v7, v118
	v_mov_b32_e32 v8, v118
	v_mov_b32_e32 v9, v118

.LBB0_345:
	s_ashr_i32 s11, s10, 31
	s_lshl_b64 s[16:17], s[10:11], 21
	s_add_u32 s16, s44, s16
	s_addc_u32 s17, s45, s17
	s_and_b64 s[20:21], s[28:29], exec
	s_cselect_b32 s1, s17, s27
	s_cselect_b32 s2, s16, s26
	s_ashr_i32 s15, s14, 31
	s_lshl_b64 s[20:21], s[14:15], 21
	s_add_u32 s20, s39, s20
	s_addc_u32 s21, s40, s21
	s_and_b64 s[28:29], s[28:29], exec
	s_cselect_b32 s11, s21, s25
	s_cselect_b32 s15, s20, s24
	s_add_u32 s19, s24, 0x100
	s_addc_u32 s23, s25, 0
	s_add_u32 s33, s26, 0x100
	v_mov_b32_e32 v6, 0
	s_addc_u32 s52, s27, 0
	s_mov_b32 s53, -2
	v_mov_b32_e32 v7, v6
	v_mov_b32_e32 v8, v6
	v_mov_b32_e32 v9, v6
	v_mov_b32_e32 v10, v6
	v_mov_b32_e32 v11, v6
	v_mov_b32_e32 v12, v6
	v_mov_b32_e32 v13, v6
	v_mov_b32_e32 v22, v6
	v_mov_b32_e32 v23, v6
	v_mov_b32_e32 v24, v6
	v_mov_b32_e32 v25, v6
	v_mov_b32_e32 v26, v6
	v_mov_b32_e32 v27, v6
	v_mov_b32_e32 v28, v6
	v_mov_b32_e32 v29, v6
	v_mov_b32_e32 v38, v6
	v_mov_b32_e32 v39, v6
	v_mov_b32_e32 v40, v6
	v_mov_b32_e32 v41, v6
	v_mov_b32_e32 v42, v6
	v_mov_b32_e32 v43, v6
	v_mov_b32_e32 v44, v6
	v_mov_b32_e32 v45, v6
	v_mov_b32_e32 v54, v6
	v_mov_b32_e32 v55, v6
	v_mov_b32_e32 v56, v6
	v_mov_b32_e32 v57, v6
	v_mov_b32_e32 v58, v6
	v_mov_b32_e32 v59, v6
	v_mov_b32_e32 v60, v6
	v_mov_b32_e32 v61, v6
	v_mov_b32_e32 v14, v6
	v_mov_b32_e32 v15, v6
	v_mov_b32_e32 v16, v6
	v_mov_b32_e32 v17, v6
	v_mov_b32_e32 v18, v6
	v_mov_b32_e32 v19, v6
	v_mov_b32_e32 v20, v6
	v_mov_b32_e32 v21, v6
	v_mov_b32_e32 v30, v6
	v_mov_b32_e32 v31, v6
	v_mov_b32_e32 v32, v6
	v_mov_b32_e32 v33, v6
	v_mov_b32_e32 v34, v6
	v_mov_b32_e32 v35, v6
	v_mov_b32_e32 v36, v6
	v_mov_b32_e32 v37, v6
	v_mov_b32_e32 v46, v6
	v_mov_b32_e32 v47, v6
	v_mov_b32_e32 v48, v6
	v_mov_b32_e32 v49, v6
	v_mov_b32_e32 v50, v6
	v_mov_b32_e32 v51, v6
	v_mov_b32_e32 v52, v6
	v_mov_b32_e32 v53, v6
	v_mov_b32_e32 v62, v6
	v_mov_b32_e32 v63, v6
	v_mov_b32_e32 v64, v6
	v_mov_b32_e32 v65, v6
	v_mov_b32_e32 v66, v6
	v_mov_b32_e32 v67, v6
	v_mov_b32_e32 v68, v6
	v_mov_b32_e32 v69, v6
	v_mov_b32_e32 v70, v6
	v_mov_b32_e32 v71, v6
	v_mov_b32_e32 v72, v6
	v_mov_b32_e32 v73, v6
	v_mov_b32_e32 v74, v6
	v_mov_b32_e32 v75, v6
	v_mov_b32_e32 v76, v6
	v_mov_b32_e32 v77, v6
	v_mov_b32_e32 v86, v6
	v_mov_b32_e32 v87, v6
	v_mov_b32_e32 v88, v6
	v_mov_b32_e32 v89, v6
	v_mov_b32_e32 v90, v6
	v_mov_b32_e32 v91, v6
	v_mov_b32_e32 v92, v6
	v_mov_b32_e32 v93, v6
	v_mov_b32_e32 v102, v6
	v_mov_b32_e32 v103, v6
	v_mov_b32_e32 v104, v6
	v_mov_b32_e32 v105, v6
	v_mov_b32_e32 v106, v6
	v_mov_b32_e32 v107, v6
	v_mov_b32_e32 v108, v6
	v_mov_b32_e32 v109, v6
	v_mov_b32_e32 v118, v6
	v_mov_b32_e32 v119, v6
	v_mov_b32_e32 v120, v6
	v_mov_b32_e32 v121, v6
	v_mov_b32_e32 v122, v6
	v_mov_b32_e32 v123, v6
	v_mov_b32_e32 v124, v6
	v_mov_b32_e32 v125, v6
	v_mov_b32_e32 v78, v6
	v_mov_b32_e32 v79, v6
	v_mov_b32_e32 v80, v6
	v_mov_b32_e32 v81, v6
	v_mov_b32_e32 v82, v6
	v_mov_b32_e32 v83, v6
	v_mov_b32_e32 v84, v6
	v_mov_b32_e32 v85, v6
	v_mov_b32_e32 v94, v6
	v_mov_b32_e32 v95, v6
	v_mov_b32_e32 v96, v6
	v_mov_b32_e32 v97, v6
	v_mov_b32_e32 v98, v6
	v_mov_b32_e32 v99, v6
	v_mov_b32_e32 v100, v6
	v_mov_b32_e32 v101, v6
	v_mov_b32_e32 v110, v6
	v_mov_b32_e32 v111, v6
	v_mov_b32_e32 v112, v6
	v_mov_b32_e32 v113, v6
	v_mov_b32_e32 v114, v6
	v_mov_b32_e32 v115, v6
	v_mov_b32_e32 v116, v6
	v_mov_b32_e32 v117, v6
	v_mov_b32_e32 v126, v6
	v_mov_b32_e32 v127, v6
	v_mov_b32_e32 v128, v6
	v_mov_b32_e32 v129, v6
	v_mov_b32_e32 v130, v6
	v_mov_b32_e32 v131, v6
	v_mov_b32_e32 v132, v6
	v_mov_b32_e32 v133, v6

.LBB0_453:
	s_ashr_i32 s21, s20, 31
	s_lshl_b64 s[24:25], s[20:21], 19
	s_add_u32 s24, s47, s24
	s_addc_u32 s25, s48, s25
	s_and_b64 s[26:27], s[16:17], exec
	s_cselect_b32 s3, s25, s37
	s_cselect_b32 s21, s24, s36
	s_ashr_i32 s23, s22, 31
	s_lshl_b64 s[26:27], s[22:23], 19
	s_add_u32 s26, s49, s26
	s_addc_u32 s27, s50, s27
	s_and_b64 s[38:39], s[16:17], exec
	s_cselect_b32 s23, s27, s35
	s_cselect_b32 s31, s26, s34
	s_add_u32 s33, s34, 0x100
	s_addc_u32 s61, s35, 0
	s_add_u32 s62, s36, 0x100
	v_mov_b32_e32 v6, 0
	s_addc_u32 s63, s37, 0
	s_mov_b32 s64, -2
	v_mov_b32_e32 v7, v6
	v_mov_b32_e32 v8, v6
	v_mov_b32_e32 v9, v6
	v_mov_b32_e32 v10, v6
	v_mov_b32_e32 v11, v6
	v_mov_b32_e32 v12, v6
	v_mov_b32_e32 v13, v6
	v_mov_b32_e32 v22, v6
	v_mov_b32_e32 v23, v6
	v_mov_b32_e32 v24, v6
	v_mov_b32_e32 v25, v6
	v_mov_b32_e32 v26, v6
	v_mov_b32_e32 v27, v6
	v_mov_b32_e32 v28, v6
	v_mov_b32_e32 v29, v6
	v_mov_b32_e32 v38, v6
	v_mov_b32_e32 v39, v6
	v_mov_b32_e32 v40, v6
	v_mov_b32_e32 v41, v6
	v_mov_b32_e32 v42, v6
	v_mov_b32_e32 v43, v6
	v_mov_b32_e32 v44, v6
	v_mov_b32_e32 v45, v6
	v_mov_b32_e32 v54, v6
	v_mov_b32_e32 v55, v6
	v_mov_b32_e32 v56, v6
	v_mov_b32_e32 v57, v6
	v_mov_b32_e32 v58, v6
	v_mov_b32_e32 v59, v6
	v_mov_b32_e32 v60, v6
	v_mov_b32_e32 v61, v6
	v_mov_b32_e32 v14, v6
	v_mov_b32_e32 v15, v6
	v_mov_b32_e32 v16, v6
	v_mov_b32_e32 v17, v6
	v_mov_b32_e32 v18, v6
	v_mov_b32_e32 v19, v6
	v_mov_b32_e32 v20, v6
	v_mov_b32_e32 v21, v6
	v_mov_b32_e32 v30, v6
	v_mov_b32_e32 v31, v6
	v_mov_b32_e32 v32, v6
	v_mov_b32_e32 v33, v6
	v_mov_b32_e32 v34, v6
	v_mov_b32_e32 v35, v6
	v_mov_b32_e32 v36, v6
	v_mov_b32_e32 v37, v6
	v_mov_b32_e32 v46, v6
	v_mov_b32_e32 v47, v6
	v_mov_b32_e32 v48, v6
	v_mov_b32_e32 v49, v6
	v_mov_b32_e32 v50, v6
	v_mov_b32_e32 v51, v6
	v_mov_b32_e32 v52, v6
	v_mov_b32_e32 v53, v6
	v_mov_b32_e32 v62, v6
	v_mov_b32_e32 v63, v6
	v_mov_b32_e32 v64, v6
	v_mov_b32_e32 v65, v6
	v_mov_b32_e32 v66, v6
	v_mov_b32_e32 v67, v6
	v_mov_b32_e32 v68, v6
	v_mov_b32_e32 v69, v6
	v_mov_b32_e32 v70, v6
	v_mov_b32_e32 v71, v6
	v_mov_b32_e32 v72, v6
	v_mov_b32_e32 v73, v6
	v_mov_b32_e32 v74, v6
	v_mov_b32_e32 v75, v6
	v_mov_b32_e32 v76, v6
	v_mov_b32_e32 v77, v6
	v_mov_b32_e32 v86, v6
	v_mov_b32_e32 v87, v6
	v_mov_b32_e32 v88, v6
	v_mov_b32_e32 v89, v6
	v_mov_b32_e32 v90, v6
	v_mov_b32_e32 v91, v6
	v_mov_b32_e32 v92, v6
	v_mov_b32_e32 v93, v6
	v_mov_b32_e32 v102, v6
	v_mov_b32_e32 v103, v6
	v_mov_b32_e32 v104, v6
	v_mov_b32_e32 v105, v6
	v_mov_b32_e32 v106, v6
	v_mov_b32_e32 v107, v6
	v_mov_b32_e32 v108, v6
	v_mov_b32_e32 v109, v6
	v_mov_b32_e32 v118, v6
	v_mov_b32_e32 v119, v6
	v_mov_b32_e32 v120, v6
	v_mov_b32_e32 v121, v6
	v_mov_b32_e32 v122, v6
	v_mov_b32_e32 v123, v6
	v_mov_b32_e32 v124, v6
	v_mov_b32_e32 v125, v6
	v_mov_b32_e32 v78, v6
	v_mov_b32_e32 v79, v6
	v_mov_b32_e32 v80, v6
	v_mov_b32_e32 v81, v6
	v_mov_b32_e32 v82, v6
	v_mov_b32_e32 v83, v6
	v_mov_b32_e32 v84, v6
	v_mov_b32_e32 v85, v6
	v_mov_b32_e32 v94, v6
	v_mov_b32_e32 v95, v6
	v_mov_b32_e32 v96, v6
	v_mov_b32_e32 v97, v6
	v_mov_b32_e32 v98, v6
	v_mov_b32_e32 v99, v6
	v_mov_b32_e32 v100, v6
	v_mov_b32_e32 v101, v6
	v_mov_b32_e32 v110, v6
	v_mov_b32_e32 v111, v6
	v_mov_b32_e32 v112, v6
	v_mov_b32_e32 v113, v6
	v_mov_b32_e32 v114, v6
	v_mov_b32_e32 v115, v6
	v_mov_b32_e32 v116, v6
	v_mov_b32_e32 v117, v6
	v_mov_b32_e32 v126, v6
	v_mov_b32_e32 v127, v6
	v_mov_b32_e32 v128, v6
	v_mov_b32_e32 v129, v6
	v_mov_b32_e32 v130, v6
	v_mov_b32_e32 v131, v6
	v_mov_b32_e32 v132, v6
	v_mov_b32_e32 v133, v6

.LBB0_479:
	s_ashr_i32 s15, s14, 31
	s_lshl_b64 s[20:21], s[14:15], 18
	s_add_u32 s20, s3, s20
	s_addc_u32 s21, s38, s21
	s_and_b64 s[22:23], s[18:19], exec
	s_cselect_b32 s15, s21, s29
	s_cselect_b32 s25, s20, s28
	s_ashr_i32 s17, s16, 31
	s_lshl_b64 s[22:23], s[16:17], 18
	s_add_u32 s22, s36, s22
	s_addc_u32 s23, s37, s23
	s_and_b64 s[30:31], s[18:19], exec
	s_cselect_b32 s17, s23, s27
	s_cselect_b32 s33, s22, s26
	s_add_u32 s52, s26, 0x100
	s_addc_u32 s53, s27, 0
	s_add_u32 s54, s28, 0x100
	v_mov_b32_e32 v6, 0
	s_addc_u32 s55, s29, 0
	s_mov_b32 s56, -2
	v_mov_b32_e32 v7, v6
	v_mov_b32_e32 v8, v6
	v_mov_b32_e32 v9, v6
	v_mov_b32_e32 v10, v6
	v_mov_b32_e32 v11, v6
	v_mov_b32_e32 v12, v6
	v_mov_b32_e32 v13, v6
	v_mov_b32_e32 v22, v6
	v_mov_b32_e32 v23, v6
	v_mov_b32_e32 v24, v6
	v_mov_b32_e32 v25, v6
	v_mov_b32_e32 v26, v6
	v_mov_b32_e32 v27, v6
	v_mov_b32_e32 v28, v6
	v_mov_b32_e32 v29, v6
	v_mov_b32_e32 v38, v6
	v_mov_b32_e32 v39, v6
	v_mov_b32_e32 v40, v6
	v_mov_b32_e32 v41, v6
	v_mov_b32_e32 v42, v6
	v_mov_b32_e32 v43, v6
	v_mov_b32_e32 v44, v6
	v_mov_b32_e32 v45, v6
	v_mov_b32_e32 v54, v6
	v_mov_b32_e32 v55, v6
	v_mov_b32_e32 v56, v6
	v_mov_b32_e32 v57, v6
	v_mov_b32_e32 v58, v6
	v_mov_b32_e32 v59, v6
	v_mov_b32_e32 v60, v6
	v_mov_b32_e32 v61, v6
	v_mov_b32_e32 v14, v6
	v_mov_b32_e32 v15, v6
	v_mov_b32_e32 v16, v6
	v_mov_b32_e32 v17, v6
	v_mov_b32_e32 v18, v6
	v_mov_b32_e32 v19, v6
	v_mov_b32_e32 v20, v6
	v_mov_b32_e32 v21, v6
	v_mov_b32_e32 v30, v6
	v_mov_b32_e32 v31, v6
	v_mov_b32_e32 v32, v6
	v_mov_b32_e32 v33, v6
	v_mov_b32_e32 v34, v6
	v_mov_b32_e32 v35, v6
	v_mov_b32_e32 v36, v6
	v_mov_b32_e32 v37, v6
	v_mov_b32_e32 v46, v6
	v_mov_b32_e32 v47, v6
	v_mov_b32_e32 v48, v6
	v_mov_b32_e32 v49, v6
	v_mov_b32_e32 v50, v6
	v_mov_b32_e32 v51, v6
	v_mov_b32_e32 v52, v6
	v_mov_b32_e32 v53, v6
	v_mov_b32_e32 v62, v6
	v_mov_b32_e32 v63, v6
	v_mov_b32_e32 v64, v6
	v_mov_b32_e32 v65, v6
	v_mov_b32_e32 v66, v6
	v_mov_b32_e32 v67, v6
	v_mov_b32_e32 v68, v6
	v_mov_b32_e32 v69, v6
	v_mov_b32_e32 v70, v6
	v_mov_b32_e32 v71, v6
	v_mov_b32_e32 v72, v6
	v_mov_b32_e32 v73, v6
	v_mov_b32_e32 v74, v6
	v_mov_b32_e32 v75, v6
	v_mov_b32_e32 v76, v6
	v_mov_b32_e32 v77, v6
	v_mov_b32_e32 v86, v6
	v_mov_b32_e32 v87, v6
	v_mov_b32_e32 v88, v6
	v_mov_b32_e32 v89, v6
	v_mov_b32_e32 v90, v6
	v_mov_b32_e32 v91, v6
	v_mov_b32_e32 v92, v6
	v_mov_b32_e32 v93, v6
	v_mov_b32_e32 v102, v6
	v_mov_b32_e32 v103, v6
	v_mov_b32_e32 v104, v6
	v_mov_b32_e32 v105, v6
	v_mov_b32_e32 v106, v6
	v_mov_b32_e32 v107, v6
	v_mov_b32_e32 v108, v6
	v_mov_b32_e32 v109, v6
	v_mov_b32_e32 v118, v6
	v_mov_b32_e32 v119, v6
	v_mov_b32_e32 v120, v6
	v_mov_b32_e32 v121, v6
	v_mov_b32_e32 v122, v6
	v_mov_b32_e32 v123, v6
	v_mov_b32_e32 v124, v6
	v_mov_b32_e32 v125, v6
	v_mov_b32_e32 v78, v6
	v_mov_b32_e32 v79, v6
	v_mov_b32_e32 v80, v6
	v_mov_b32_e32 v81, v6
	v_mov_b32_e32 v82, v6
	v_mov_b32_e32 v83, v6
	v_mov_b32_e32 v84, v6
	v_mov_b32_e32 v85, v6
	v_mov_b32_e32 v94, v6
	v_mov_b32_e32 v95, v6
	v_mov_b32_e32 v96, v6
	v_mov_b32_e32 v97, v6
	v_mov_b32_e32 v98, v6
	v_mov_b32_e32 v99, v6
	v_mov_b32_e32 v100, v6
	v_mov_b32_e32 v101, v6
	v_mov_b32_e32 v110, v6
	v_mov_b32_e32 v111, v6
	v_mov_b32_e32 v112, v6
	v_mov_b32_e32 v113, v6
	v_mov_b32_e32 v114, v6
	v_mov_b32_e32 v115, v6
	v_mov_b32_e32 v116, v6
	v_mov_b32_e32 v117, v6
	v_mov_b32_e32 v126, v6
	v_mov_b32_e32 v127, v6
	v_mov_b32_e32 v128, v6
	v_mov_b32_e32 v129, v6
	v_mov_b32_e32 v130, v6
	v_mov_b32_e32 v131, v6
	v_mov_b32_e32 v132, v6
	v_mov_b32_e32 v133, v6

.LBB0_535:
	s_ashr_i32 s7, s6, 31
	s_lshl_b64 s[10:11], s[6:7], 18
	s_add_u32 s10, s3, s10
	s_addc_u32 s11, s30, s11
	s_and_b64 s[12:13], s[22:23], exec
	s_cselect_b32 s7, s11, s21
	s_cselect_b32 s41, s10, s20
	s_ashr_i32 s9, s8, 31
	s_lshl_b64 s[12:13], s[8:9], 18
	s_add_u32 s12, s36, s12
	s_addc_u32 s13, s37, s13
	s_and_b64 s[22:23], s[22:23], exec
	s_cselect_b32 s9, s13, s19
	s_cselect_b32 s42, s12, s18
	s_add_u32 s43, s18, 0x100
	s_addc_u32 s44, s19, 0
	s_add_u32 s45, s20, 0x100
	v_mov_b32_e32 v6, 0
	s_addc_u32 s46, s21, 0
	s_mov_b32 s47, -2
	v_mov_b32_e32 v7, v6
	v_mov_b32_e32 v8, v6
	v_mov_b32_e32 v9, v6
	v_mov_b32_e32 v10, v6
	v_mov_b32_e32 v11, v6
	v_mov_b32_e32 v12, v6
	v_mov_b32_e32 v13, v6
	v_mov_b32_e32 v14, v6
	v_mov_b32_e32 v15, v6
	v_mov_b32_e32 v16, v6
	v_mov_b32_e32 v17, v6
	v_mov_b32_e32 v22, v6
	v_mov_b32_e32 v23, v6
	v_mov_b32_e32 v24, v6
	v_mov_b32_e32 v25, v6
	v_mov_b32_e32 v30, v6
	v_mov_b32_e32 v31, v6
	v_mov_b32_e32 v32, v6
	v_mov_b32_e32 v33, v6
	v_mov_b32_e32 v38, v6
	v_mov_b32_e32 v39, v6
	v_mov_b32_e32 v40, v6
	v_mov_b32_e32 v41, v6
	v_mov_b32_e32 v46, v6
	v_mov_b32_e32 v47, v6
	v_mov_b32_e32 v48, v6
	v_mov_b32_e32 v49, v6
	v_mov_b32_e32 v54, v6
	v_mov_b32_e32 v55, v6
	v_mov_b32_e32 v56, v6
	v_mov_b32_e32 v57, v6
	v_mov_b32_e32 v18, v6
	v_mov_b32_e32 v19, v6
	v_mov_b32_e32 v20, v6
	v_mov_b32_e32 v21, v6
	v_mov_b32_e32 v26, v6
	v_mov_b32_e32 v27, v6
	v_mov_b32_e32 v28, v6
	v_mov_b32_e32 v29, v6
	v_mov_b32_e32 v34, v6
	v_mov_b32_e32 v35, v6
	v_mov_b32_e32 v36, v6
	v_mov_b32_e32 v37, v6
	v_mov_b32_e32 v42, v6
	v_mov_b32_e32 v43, v6
	v_mov_b32_e32 v44, v6
	v_mov_b32_e32 v45, v6
	v_mov_b32_e32 v50, v6
	v_mov_b32_e32 v51, v6
	v_mov_b32_e32 v52, v6
	v_mov_b32_e32 v53, v6
	v_mov_b32_e32 v58, v6
	v_mov_b32_e32 v59, v6
	v_mov_b32_e32 v60, v6
	v_mov_b32_e32 v61, v6
	v_mov_b32_e32 v62, v6
	v_mov_b32_e32 v63, v6
	v_mov_b32_e32 v64, v6
	v_mov_b32_e32 v65, v6
	v_mov_b32_e32 v66, v6
	v_mov_b32_e32 v67, v6
	v_mov_b32_e32 v68, v6
	v_mov_b32_e32 v69, v6
	v_mov_b32_e32 v70, v6
	v_mov_b32_e32 v71, v6
	v_mov_b32_e32 v72, v6
	v_mov_b32_e32 v73, v6
	v_mov_b32_e32 v74, v6
	v_mov_b32_e32 v75, v6
	v_mov_b32_e32 v76, v6
	v_mov_b32_e32 v77, v6
	v_mov_b32_e32 v78, v6
	v_mov_b32_e32 v79, v6
	v_mov_b32_e32 v80, v6
	v_mov_b32_e32 v81, v6
	v_mov_b32_e32 v86, v6
	v_mov_b32_e32 v87, v6
	v_mov_b32_e32 v88, v6
	v_mov_b32_e32 v89, v6
	v_mov_b32_e32 v94, v6
	v_mov_b32_e32 v95, v6
	v_mov_b32_e32 v96, v6
	v_mov_b32_e32 v97, v6
	v_mov_b32_e32 v102, v6
	v_mov_b32_e32 v103, v6
	v_mov_b32_e32 v104, v6
	v_mov_b32_e32 v105, v6
	v_mov_b32_e32 v110, v6
	v_mov_b32_e32 v111, v6
	v_mov_b32_e32 v112, v6
	v_mov_b32_e32 v113, v6
	v_mov_b32_e32 v118, v6
	v_mov_b32_e32 v119, v6
	v_mov_b32_e32 v120, v6
	v_mov_b32_e32 v121, v6
	v_mov_b32_e32 v82, v6
	v_mov_b32_e32 v83, v6
	v_mov_b32_e32 v84, v6
	v_mov_b32_e32 v85, v6
	v_mov_b32_e32 v90, v6
	v_mov_b32_e32 v91, v6
	v_mov_b32_e32 v92, v6
	v_mov_b32_e32 v93, v6
	v_mov_b32_e32 v98, v6
	v_mov_b32_e32 v99, v6
	v_mov_b32_e32 v100, v6
	v_mov_b32_e32 v101, v6
	v_mov_b32_e32 v106, v6
	v_mov_b32_e32 v107, v6
	v_mov_b32_e32 v108, v6
	v_mov_b32_e32 v109, v6
	v_mov_b32_e32 v114, v6
	v_mov_b32_e32 v115, v6
	v_mov_b32_e32 v116, v6
	v_mov_b32_e32 v117, v6
	v_mov_b32_e32 v122, v6
	v_mov_b32_e32 v123, v6
	v_mov_b32_e32 v124, v6
	v_mov_b32_e32 v125, v6
	v_mov_b32_e32 v126, v6
	v_mov_b32_e32 v127, v6
	v_mov_b32_e32 v128, v6
	v_mov_b32_e32 v129, v6
	v_mov_b32_e32 v130, v6
	v_mov_b32_e32 v131, v6
	v_mov_b32_e32 v132, v6
	v_mov_b32_e32 v133, v6

.LBB0_711:
	s_xor_b64 s[80:81], s[0:1], -1
	s_and_b64 s[0:1], s[0:1], exec
	v_mov_b32_e32 v1, v0
	s_cselect_b32 s0, s93, s3
	v_readfirstlane_b32 s1, v1
	s_ashr_i32 s1, s1, 6
	s_lshl_b32 s2, s0, 8
	s_lshl_b32 s95, s1, 5
	v_and_b32_e32 v24, 31, v1
	s_add_i32 s95, s95, s2
	v_or_b32_e32 v2, s95, v24
	v_ashrrev_i32_e32 v3, 31, v2
	v_and_b32_e32 v5, 63, v1
	v_bfe_u32 v25, v1, 5, 1
	v_lshlrev_b64 v[134:135], 12, v[2:3]
	v_lshl_add_u64 v[6:7], s[38:39], 0, v[134:135]
	v_lshlrev_b32_e32 v8, 4, v25
	v_mov_b32_e32 v9, v4
	s_lshl_b32 s6, s1, 11
	v_lshlrev_b32_e32 v3, 4, v5
	v_lshl_add_u64 v[6:7], v[6:7], 0, v[8:9]
	v_or_b32_e32 v5, s6, v3
	global_load_dwordx4 v[102:105], v[6:7], off
	global_load_dwordx4 v[106:109], v[6:7], off offset:32
	global_load_dwordx4 v[110:113], v[6:7], off offset:64
	global_load_dwordx4 v[114:117], v[6:7], off offset:96
	global_load_dwordx4 v[118:121], v[6:7], off offset:128
	global_load_dwordx4 v[122:125], v[6:7], off offset:160
	global_load_dwordx4 v[126:129], v[6:7], off offset:192
	global_load_dwordx4 v[130:133], v[6:7], off offset:224
	v_ashrrev_i32_e32 v6, 31, v5
	v_add_u32_sdwa v6, v5, v6 dst_sel:DWORD dst_unused:UNUSED_PAD src0_sel:DWORD src1_sel:BYTE_3
	v_ashrrev_i32_e32 v6, 8, v6
	v_mul_i32_i24_e32 v7, 0x100, v6
	v_sub_u32_e32 v7, v5, v7
	v_ashrrev_i32_e32 v9, 4, v7
	v_bitop3_b32 v10, v9, v6, 15 bitop3:0x78
	v_ashrrev_i32_e32 v7, 31, v6
	v_lshlrev_b64 v[6:7], 12, v[6:7]
	v_lshlrev_b32_e32 v10, 3, v10
	s_bfe_i32 s2, s1, 0x10014
	v_lshl_add_u64 v[6:7], s[72:73], 0, v[6:7]
	v_ashrrev_i32_e32 v11, 31, v10
	s_lshr_b32 s2, s2, 24
	v_lshl_add_u64 v[6:7], v[10:11], 1, v[6:7]
	v_add_u32_e32 v10, s2, v5
	v_add_u32_e32 v10, 0x400, v10
	v_ashrrev_i32_e32 v10, 8, v10
	v_bitop3_b32 v9, v10, v9, 15 bitop3:0x6c
	v_ashrrev_i32_e32 v11, 31, v10
	v_lshlrev_b64 v[10:11], 12, v[10:11]
	v_lshlrev_b32_e32 v12, 3, v9
	v_lshl_add_u64 v[10:11], s[72:73], 0, v[10:11]
	v_ashrrev_i32_e32 v13, 31, v12
	v_lshl_add_u64 v[10:11], v[12:13], 1, v[10:11]
	v_ashrrev_i32_e32 v12, 8, v5
	v_lshlrev_b32_e32 v5, 2, v12
	s_lshl_b32 s1, s1, 1
	v_and_b32_e32 v9, 15, v1
	v_and_b32_e32 v5, 12, v5
	s_and_b32 s1, s1, 2
	v_ashrrev_i32_e32 v13, 31, v12
	v_bitop3_b32 v5, v5, v9, s1 bitop3:0x36
	v_lshlrev_b64 v[12:13], 12, v[12:13]
	s_or_b32 s1, s6, 0x400
	v_lshl_add_u64 v[12:13], s[74:75], 0, v[12:13]
	v_lshlrev_b32_e32 v14, 4, v5
	v_mov_b32_e32 v15, v4
	v_or_b32_e32 v3, s1, v3
	v_lshl_add_u64 v[12:13], v[12:13], 0, v[14:15]
	v_ashrrev_i32_e32 v14, 8, v3
	v_lshlrev_b32_e32 v3, 2, v14
	s_add_i32 s92, s6, 0
	v_and_b32_e32 v3, 12, v3
	s_bfe_u32 s1, s1, 0x2000a
	v_ashrrev_i32_e32 v15, 31, v14
	s_mov_b32 m0, s92
	s_add_i32 s2, 0, 0x12000
	v_bitop3_b32 v3, v3, v9, s1 bitop3:0x36
	v_lshlrev_b64 v[14:15], 12, v[14:15]
	global_load_lds_dwordx4 v[6:7], off
	s_add_i32 m0, s92, 0x400
	s_add_i32 s87, s2, s6
	v_lshl_add_u64 v[14:15], s[74:75], 0, v[14:15]
	v_lshlrev_b32_e32 v16, 4, v3
	v_mov_b32_e32 v17, v4
	global_load_lds_dwordx4 v[10:11], off
	s_mov_b32 m0, s87
	v_lshl_add_u64 v[14:15], v[14:15], 0, v[16:17]
	global_load_lds_dwordx4 v[12:13], off
	s_add_i32 m0, s87, 0x400
	v_lshl_add_u64 v[16:17], v[6:7], 0, s[4:5]
	global_load_lds_dwordx4 v[14:15], off
	s_add_i32 m0, s92, 0x4000
	v_lshl_add_u64 v[18:19], v[10:11], 0, s[4:5]
	global_load_lds_dwordx4 v[16:17], off
	s_add_i32 m0, s92, 0x4400
	v_lshl_add_u64 v[20:21], v[12:13], 0, s[4:5]
	global_load_lds_dwordx4 v[18:19], off
	s_add_i32 m0, s92, 0x16000
	v_lshl_add_u64 v[22:23], v[14:15], 0, s[4:5]
	global_load_lds_dwordx4 v[20:21], off
	s_add_i32 m0, s92, 0x16400
	s_lshl_b32 s1, s0, 2
	global_load_lds_dwordx4 v[22:23], off
	v_lshrrev_b32_e32 v9, 3, v1
	v_bfe_u32 v16, v1, 1, 1
	v_lshlrev_b32_e32 v136, 3, v25
	v_bfe_u32 v3, v1, 2, 2
	v_and_or_b32 v9, v9, 2, v16
	v_lshlrev_b32_e32 v17, 4, v1
	s_or_b32 s94, s1, 2
	s_movk_i32 s1, 0xf0
	v_or_b32_e32 v5, v136, v3
	v_lshlrev_b32_e32 v9, 4, v9
	v_lshl_add_u64 v[138:139], v[6:7], 0, s[96:97]
	v_and_b32_e32 v6, 0xf0, v17
	v_bitop3_b32 v146, v8, v17, s1 bitop3:0x78
	s_movk_i32 s1, 0x80
	v_lshlrev_b32_e32 v5, 8, v5
	v_lshlrev_b32_e32 v16, 3, v1
	v_bitop3_b32 v9, v9, v1, 32 bitop3:0x78
	v_lshlrev_b32_e32 v3, 6, v3
	v_bitop3_b32 v150, v8, v6, s1 bitop3:0x36
	s_movk_i32 s1, 0xa0
	s_waitcnt vmcnt(4)
	v_lshlrev_b32_e32 v1, 2, v25
	v_bitop3_b32 v151, v8, v6, s1 bitop3:0x36
	s_movk_i32 s1, 0xe0
	v_or3_b32 v3, v3, v5, v9
	v_and_or_b32 v5, v16, 8, s2
	v_mov_b32_e32 v16, v4
	v_mov_b32_e32 v17, v4
	v_lshl_add_u64 v[142:143], v[10:11], 0, s[96:97]
	v_lshl_add_u64 v[140:141], v[12:13], 0, s[96:97]
	v_lshl_add_u64 v[144:145], v[14:15], 0, s[96:97]
	s_waitcnt lgkmcnt(0)
	s_barrier
	v_lshl_add_u32 v137, v24, 8, 0
	v_bitop3_b32 v147, v8, v6, 32 bitop3:0x36
	v_bitop3_b32 v148, v8, v6, 64 bitop3:0x36
	v_bitop3_b32 v149, v8, v6, s89 bitop3:0x36
	v_bitop3_b32 v152, v8, v6, s88 bitop3:0x36
	v_bitop3_b32 v153, v8, v6, s1 bitop3:0x36
	v_add_u32_e32 v154, v5, v3
	v_add_u32_e32 v155, 0, v8
	v_sub_u32_e32 v156, v2, v1
	v_mov_b32_e32 v2, v4
	v_mov_b32_e32 v3, v4
	v_mov_b32_e32 v5, v4
	v_mov_b32_e32 v6, v4
	v_mov_b32_e32 v7, v4
	v_mov_b32_e32 v8, v4
	v_mov_b32_e32 v9, v4
	v_mov_b32_e32 v10, v4
	v_mov_b32_e32 v11, v4
	v_mov_b32_e32 v12, v4
	v_mov_b32_e32 v13, v4
	v_mov_b32_e32 v14, v4
	v_mov_b32_e32 v15, v4
	v_mov_b64_e32 v[68:69], v[16:17]
	v_mov_b64_e32 v[52:53], v[16:17]
	v_mov_b64_e32 v[36:37], v[16:17]
	s_lshl_b32 s33, s0, 10
	v_mov_b64_e32 v[66:67], v[14:15]
	v_mov_b64_e32 v[64:65], v[12:13]
	v_mov_b64_e32 v[62:63], v[10:11]
	v_mov_b64_e32 v[60:61], v[8:9]
	v_mov_b64_e32 v[58:59], v[6:7]
	v_mov_b64_e32 v[56:57], v[4:5]
	v_mov_b64_e32 v[54:55], v[2:3]
	v_mov_b64_e32 v[50:51], v[14:15]
	v_mov_b64_e32 v[48:49], v[12:13]
	v_mov_b64_e32 v[46:47], v[10:11]
	v_mov_b64_e32 v[44:45], v[8:9]
	v_mov_b64_e32 v[42:43], v[6:7]
	v_mov_b64_e32 v[40:41], v[4:5]
	v_mov_b64_e32 v[38:39], v[2:3]
	v_mov_b64_e32 v[34:35], v[14:15]
	v_mov_b64_e32 v[32:33], v[12:13]
	v_mov_b64_e32 v[30:31], v[10:11]
	v_mov_b64_e32 v[28:29], v[8:9]
	v_mov_b64_e32 v[26:27], v[6:7]
	v_mov_b64_e32 v[24:25], v[4:5]
	v_mov_b64_e32 v[22:23], v[2:3]
	v_mov_b64_e32 v[20:21], v[16:17]
	s_mov_b32 s85, 63
	s_mov_b32 s91, 2
	s_mov_b32 s36, 1
	s_or_b32 s84, s95, 31
	s_addk_i32 s33, 0x400
	s_mov_b32 s70, 0
	v_mov_b32_e32 v158, 0
	v_mov_b32_e32 v157, 0xf149f2ca
	v_mov_b64_e32 v[18:19], v[14:15]
	v_mov_b64_e32 v[16:17], v[12:13]
	v_mov_b64_e32 v[14:15], v[10:11]
	v_mov_b64_e32 v[12:13], v[8:9]
	v_mov_b64_e32 v[10:11], v[6:7]
	v_mov_b64_e32 v[8:9], v[4:5]
	v_mov_b64_e32 v[6:7], v[2:3]
	s_mov_b32 s0, 0
	s_mov_b32 s71, 0
.LBB0_712:
	s_cmp_ge_u32 s71, s94
	s_cselect_b64 s[82:83], -1, 0
	s_mov_b32 s89, s0
	s_and_b64 vcc, exec, s[82:83]
	s_cbranch_vccz .LBB0_719
	s_sub_i32 s0, s85, 63
	s_cmp_gt_i32 s0, s84
	s_cbranch_scc0 .LBB0_720

.LBB0_728:
	v_mov_b32_e32 v5, v0
	s_and_b64 s[14:15], s[16:17], exec
	s_cselect_b32 s19, s93, s3
	v_readfirstlane_b32 s18, v5
	s_ashr_i32 s21, s18, 6
	s_lshl_b32 s14, s19, 8
	s_lshl_b32 s15, s21, 5
	v_and_b32_e32 v1, 31, v5
	s_add_i32 s15, s15, s14
	v_bfe_u32 v16, v5, 5, 1
	v_or_b32_e32 v150, s15, v1
	v_mov_b64_e32 v[2:3], s[0:1]
	s_movk_i32 s14, 0x1800
	v_mad_i64_i32 v[6:7], s[14:15], v150, s14, v[2:3]
	v_lshlrev_b32_e32 v2, 4, v16
	v_mov_b32_e32 v3, v4
	v_lshl_add_u64 v[6:7], v[6:7], 0, v[2:3]
	global_load_dwordx4 v[102:105], v[6:7], off
	global_load_dwordx4 v[106:109], v[6:7], off offset:32
	global_load_dwordx4 v[110:113], v[6:7], off offset:64
	global_load_dwordx4 v[114:117], v[6:7], off offset:96
	global_load_dwordx4 v[118:121], v[6:7], off offset:128
	global_load_dwordx4 v[122:125], v[6:7], off offset:160
	global_load_dwordx4 v[126:129], v[6:7], off offset:192
	global_load_dwordx4 v[130:133], v[6:7], off offset:224
	global_load_dwordx4 v[134:137], v[6:7], off offset:256
	global_load_dwordx4 v[138:141], v[6:7], off offset:288
	global_load_dwordx4 v[142:145], v[6:7], off offset:320
	global_load_dwordx4 v[146:149], v[6:7], off offset:352
	v_and_b32_e32 v3, 63, v5
	v_lshlrev_b32_e32 v3, 4, v3
	s_mul_i32 s20, s21, 0xc00
	v_or_b32_e32 v6, s20, v3
	s_mov_b32 s14, 0x2aaaaaab
	v_mul_hi_i32 v7, v6, s14
	v_lshrrev_b32_e32 v8, 31, v7
	v_ashrrev_i32_e32 v7, 6, v7
	v_add_u32_e32 v8, v7, v8
	v_mul_i32_i24_e32 v7, 0x180, v8
	v_sub_u32_e32 v6, v6, v7
	v_ashrrev_i32_e32 v6, 4, v6
	v_lshrrev_b32_e32 v7, 1, v8
	v_bitop3_b32 v6, v7, v6, 7 bitop3:0x6c
	v_cmp_gt_i32_e32 vcc, 16, v6
	v_ashrrev_i32_e32 v9, 31, v8
	v_lshlrev_b32_e32 v10, 3, v6
	s_and_saveexec_b64 s[14:15], vcc
	s_xor_b64 s[14:15], exec, s[14:15]
	v_lshlrev_b64 v[6:7], 13, v[8:9]
	v_lshl_add_u64 v[6:7], s[6:7], 0, v[6:7]
	v_ashrrev_i32_e32 v11, 31, v10
	v_lshl_add_u64 v[6:7], v[10:11], 1, v[6:7]
	s_or_saveexec_b64 s[14:15], s[14:15]
	v_mov_b64_e32 v[152:153], 0x80000
	s_xor_b64 exec, exec, s[14:15]
	v_lshlrev_b64 v[6:7], 7, v[8:9]
	v_lshl_add_u64 v[6:7], s[8:9], 0, v[6:7]
	v_mov_b32_e32 v11, v4
	s_movk_i32 s22, 0xff00
	v_lshl_add_u64 v[6:7], v[10:11], 1, v[6:7]
	s_mov_b32 s23, -1
	v_lshl_add_u64 v[6:7], v[6:7], 0, s[22:23]
	v_mov_b64_e32 v[152:153], 0x2000
	s_or_b64 exec, exec, s[14:15]
	s_add_i32 s14, s20, 0x400
	v_or_b32_e32 v8, s14, v3
	s_mov_b32 s14, 0x2aaaaaab
	v_mul_hi_i32 v9, v8, s14
	v_lshrrev_b32_e32 v10, 31, v9
	v_ashrrev_i32_e32 v9, 6, v9
	v_add_u32_e32 v10, v9, v10
	v_mul_i32_i24_e32 v9, 0x180, v10
	v_sub_u32_e32 v8, v8, v9
	v_ashrrev_i32_e32 v8, 4, v8
	v_lshrrev_b32_e32 v9, 1, v10
	v_bitop3_b32 v8, v9, v8, 7 bitop3:0x6c
	v_cmp_gt_i32_e32 vcc, 16, v8
	v_ashrrev_i32_e32 v11, 31, v10
	v_lshlrev_b32_e32 v12, 3, v8
	s_and_saveexec_b64 s[14:15], vcc
	s_xor_b64 s[14:15], exec, s[14:15]
	v_lshlrev_b64 v[8:9], 13, v[10:11]
	v_lshl_add_u64 v[8:9], s[6:7], 0, v[8:9]
	v_ashrrev_i32_e32 v13, 31, v12
	v_lshl_add_u64 v[8:9], v[12:13], 1, v[8:9]
	s_or_saveexec_b64 s[14:15], s[14:15]
	v_mov_b64_e32 v[154:155], 0x80000
	s_xor_b64 exec, exec, s[14:15]
	v_lshlrev_b64 v[8:9], 7, v[10:11]
	v_lshl_add_u64 v[8:9], s[8:9], 0, v[8:9]
	v_mov_b32_e32 v13, v4
	s_movk_i32 s22, 0xff00
	v_lshl_add_u64 v[8:9], v[12:13], 1, v[8:9]
	s_mov_b32 s23, -1
	v_lshl_add_u64 v[8:9], v[8:9], 0, s[22:23]
	v_mov_b64_e32 v[154:155], 0x2000
	s_or_b64 exec, exec, s[14:15]
	s_add_i32 s14, s20, 0x800
	v_or_b32_e32 v10, s14, v3
	s_mov_b32 s14, 0x2aaaaaab
	v_mul_hi_i32 v11, v10, s14
	v_lshrrev_b32_e32 v12, 31, v11
	v_ashrrev_i32_e32 v11, 6, v11
	v_add_u32_e32 v12, v11, v12
	v_mul_i32_i24_e32 v11, 0x180, v12
	v_sub_u32_e32 v10, v10, v11
	v_ashrrev_i32_e32 v10, 4, v10
	v_lshrrev_b32_e32 v11, 1, v12
	v_bitop3_b32 v10, v11, v10, 7 bitop3:0x6c
	v_cmp_gt_i32_e32 vcc, 16, v10
	v_ashrrev_i32_e32 v13, 31, v12
	v_lshlrev_b32_e32 v14, 3, v10
	s_and_saveexec_b64 s[14:15], vcc
	s_xor_b64 s[14:15], exec, s[14:15]
	v_lshlrev_b64 v[10:11], 13, v[12:13]
	v_lshl_add_u64 v[10:11], s[6:7], 0, v[10:11]
	v_ashrrev_i32_e32 v15, 31, v14
	v_lshl_add_u64 v[10:11], v[14:15], 1, v[10:11]
	s_or_saveexec_b64 s[14:15], s[14:15]
	v_mov_b64_e32 v[156:157], 0x80000
	s_xor_b64 exec, exec, s[14:15]
	v_lshlrev_b64 v[10:11], 7, v[12:13]
	v_lshl_add_u64 v[10:11], s[8:9], 0, v[10:11]
	v_mov_b32_e32 v15, v4
	s_movk_i32 s22, 0xff00
	v_lshl_add_u64 v[10:11], v[14:15], 1, v[10:11]
	s_mov_b32 s23, -1
	v_lshl_add_u64 v[10:11], v[10:11], 0, s[22:23]
	v_mov_b64_e32 v[156:157], 0x2000
	s_or_b64 exec, exec, s[14:15]
	s_lshl_b32 s14, s21, 11
	v_or_b32_e32 v12, s14, v3
	v_ashrrev_i32_e32 v12, 8, v12
	v_lshlrev_b32_e32 v13, 2, v12
	s_lshl_b32 s15, s21, 1
	v_and_b32_e32 v17, 15, v5
	v_and_b32_e32 v13, 12, v13
	s_and_b32 s15, s15, 2
	v_bitop3_b32 v14, v13, v17, s15 bitop3:0x36
	s_or_b32 s15, s14, 0x400
	v_or_b32_e32 v3, s15, v3
	v_ashrrev_i32_e32 v18, 8, v3
	v_ashrrev_i32_e32 v13, 31, v12
	v_lshlrev_b32_e32 v3, 2, v18
	s_add_i32 s20, s20, 0
	v_lshlrev_b64 v[12:13], 13, v[12:13]
	v_and_b32_e32 v3, 12, v3
	s_bfe_u32 s15, s15, 0x2000a
	v_ashrrev_i32_e32 v19, 31, v18
	s_mov_b32 m0, s20
	v_lshl_add_u64 v[12:13], s[6:7], 0, v[12:13]
	v_lshlrev_b32_e32 v14, 4, v14
	v_mov_b32_e32 v15, v4
	v_bitop3_b32 v3, v3, v17, s15 bitop3:0x36
	v_lshlrev_b64 v[18:19], 13, v[18:19]
	global_load_lds_dwordx4 v[6:7], off
	s_add_i32 m0, s20, 0x400
	v_lshl_add_u64 v[12:13], v[12:13], 0, v[14:15]
	s_mov_b64 s[22:23], 0x100
	v_lshl_add_u64 v[18:19], s[6:7], 0, v[18:19]
	v_lshlrev_b32_e32 v20, 4, v3
	v_mov_b32_e32 v21, v4
	global_load_lds_dwordx4 v[8:9], off
	s_add_i32 m0, s20, 0x800
	s_add_i32 s21, s2, s14
	v_lshl_add_u64 v[14:15], v[12:13], 0, s[22:23]
	v_lshl_add_u64 v[18:19], v[18:19], 0, v[20:21]
	global_load_lds_dwordx4 v[10:11], off
	s_mov_b32 m0, s21
	v_lshl_add_u64 v[20:21], v[18:19], 0, s[22:23]
	global_load_lds_dwordx4 v[14:15], off
	s_add_i32 m0, s21, 0x400
	v_lshl_add_u64 v[6:7], v[6:7], 0, v[152:153]
	global_load_lds_dwordx4 v[20:21], off
	s_add_i32 m0, s20, 0x6000
	v_lshl_add_u64 v[8:9], v[8:9], 0, v[154:155]
	global_load_lds_dwordx4 v[6:7], off
	s_add_i32 m0, s20, 0x6400
	v_lshl_add_u64 v[10:11], v[10:11], 0, v[156:157]
	s_mov_b64 s[22:23], 0x80100
	global_load_lds_dwordx4 v[8:9], off
	s_add_i32 m0, s20, 0x6800
	s_add_i32 s14, s14, 0
	v_lshl_add_u64 v[14:15], v[12:13], 0, s[22:23]
	global_load_lds_dwordx4 v[10:11], off
	s_add_i32 m0, s14, 0x16000
	v_lshl_add_u64 v[20:21], v[18:19], 0, s[22:23]
	global_load_lds_dwordx4 v[14:15], off
	s_add_i32 m0, s14, 0x16400
	s_xor_b64 s[14:15], s[16:17], -1
	global_load_lds_dwordx4 v[20:21], off
	s_mov_b64 s[16:17], 0x100100
	v_lshlrev_b32_e32 v158, 3, v16
	v_lshrrev_b32_e32 v15, 3, v5
	v_bfe_u32 v16, v5, 1, 1
	v_lshl_add_u64 v[166:167], v[12:13], 0, s[16:17]
	v_lshl_add_u64 v[168:169], v[18:19], 0, s[16:17]
	s_movk_i32 s16, 0x180
	v_and_or_b32 v15, v15, 2, v16
	v_lshlrev_b32_e32 v16, 3, v5
	v_mad_u32_u24 v1, v1, s16, 0
	s_movk_i32 s16, 0x70
	v_lshl_add_u64 v[160:161], v[6:7], 0, v[152:153]
	v_and_b32_e32 v6, 0x70, v16
	v_bitop3_b32 v159, v2, v16, s16 bitop3:0x78
	s_movk_i32 s16, 0x80
	v_bitop3_b32 v173, v2, v6, s16 bitop3:0x36
	s_movk_i32 s16, 0xa0
	v_bitop3_b32 v174, v2, v6, s16 bitop3:0x36
	s_movk_i32 s16, 0xe0
	v_bfe_u32 v3, v5, 2, 2
	v_bitop3_b32 v176, v2, v6, s16 bitop3:0x36
	s_movk_i32 s16, 0x120
	v_or_b32_e32 v14, v158, v3
	v_lshlrev_b32_e32 v15, 4, v15
	v_bitop3_b32 v178, v2, v6, s16 bitop3:0x36
	s_movk_i32 s16, 0x140
	v_lshlrev_b32_e32 v14, 8, v14
	v_bitop3_b32 v5, v15, v5, 32 bitop3:0x78
	v_lshlrev_b32_e32 v3, 6, v3
	v_bitop3_b32 v179, v2, v6, s16 bitop3:0x36
	s_movk_i32 s16, 0x160
	s_waitcnt vmcnt(5)
	v_bitop3_b32 v170, v2, v6, 32 bitop3:0x36
	v_bitop3_b32 v171, v2, v6, 64 bitop3:0x36
	v_bitop3_b32 v172, v2, v6, s89 bitop3:0x36
	v_bitop3_b32 v175, v2, v6, s87 bitop3:0x36
	v_bitop3_b32 v177, v2, v6, s92 bitop3:0x36
	v_bitop3_b32 v180, v2, v6, s16 bitop3:0x36
	v_or3_b32 v2, v3, v14, v5
	v_and_or_b32 v3, v16, 8, s2
	v_mov_b32_e32 v16, v4
	v_mov_b32_e32 v17, v4
	v_lshl_add_u64 v[162:163], v[8:9], 0, v[154:155]
	v_lshl_add_u64 v[164:165], v[10:11], 0, v[156:157]
	s_waitcnt lgkmcnt(0)
	s_barrier
	v_add_u32_e32 v181, v3, v2
	v_mov_b32_e32 v2, v4
	v_mov_b32_e32 v3, v4
	v_mov_b32_e32 v5, v4
	v_mov_b32_e32 v6, v4
	v_mov_b32_e32 v7, v4
	v_mov_b32_e32 v8, v4
	v_mov_b32_e32 v9, v4
	v_mov_b32_e32 v10, v4
	v_mov_b32_e32 v11, v4
	v_mov_b32_e32 v12, v4
	v_mov_b32_e32 v13, v4
	v_mov_b32_e32 v14, v4
	v_mov_b32_e32 v15, v4
	v_mov_b64_e32 v[68:69], v[16:17]
	v_mov_b64_e32 v[52:53], v[16:17]
	v_mov_b64_e32 v[36:37], v[16:17]
	s_lshl_b32 s26, s19, 2
	s_ashr_i32 s25, s18, 7
	v_mov_b64_e32 v[66:67], v[14:15]
	v_mov_b64_e32 v[64:65], v[12:13]
	v_mov_b64_e32 v[62:63], v[10:11]
	v_mov_b64_e32 v[60:61], v[8:9]
	v_mov_b64_e32 v[58:59], v[6:7]
	v_mov_b64_e32 v[56:57], v[4:5]
	v_mov_b64_e32 v[54:55], v[2:3]
	v_mov_b64_e32 v[50:51], v[14:15]
	v_mov_b64_e32 v[48:49], v[12:13]
	v_mov_b64_e32 v[46:47], v[10:11]
	v_mov_b64_e32 v[44:45], v[8:9]
	v_mov_b64_e32 v[42:43], v[6:7]
	v_mov_b64_e32 v[40:41], v[4:5]
	v_mov_b64_e32 v[38:39], v[2:3]
	v_mov_b64_e32 v[34:35], v[14:15]
	v_mov_b64_e32 v[32:33], v[12:13]
	v_mov_b64_e32 v[30:31], v[10:11]
	v_mov_b64_e32 v[28:29], v[8:9]
	v_mov_b64_e32 v[26:27], v[6:7]
	v_mov_b64_e32 v[24:25], v[4:5]
	v_mov_b64_e32 v[22:23], v[2:3]
	v_mov_b64_e32 v[20:21], v[16:17]
	v_ashrrev_i32_e32 v151, 31, v150
	s_mov_b32 s22, 2
	s_mov_b32 s23, 1
	s_or_b32 s24, s26, 2
	s_add_i32 s25, s25, s26
	s_add_i32 s26, s26, 4
	s_mov_b32 s16, 0
	v_mov_b32_e32 v183, 0
	v_mov_b32_e32 v182, 0xf149f2ca
	v_mov_b64_e32 v[18:19], v[14:15]
	v_mov_b64_e32 v[16:17], v[12:13]
	v_mov_b64_e32 v[14:15], v[10:11]
	v_mov_b64_e32 v[12:13], v[8:9]
	v_mov_b64_e32 v[10:11], v[6:7]
	v_mov_b64_e32 v[8:9], v[4:5]
	v_mov_b64_e32 v[6:7], v[2:3]
	s_mov_b32 s27, 0
.LBB0_741:
	s_cmp_ge_u32 s27, s24
	s_mov_b32 s28, s16
	s_cselect_b64 s[16:17], -1, 0
	s_and_b64 vcc, exec, s[16:17]
	s_cbranch_vccz .LBB0_748
	s_cmp_gt_i32 s27, s25
	s_cbranch_scc0 .LBB0_749
